# combo1 + 64-bit accumulator zeroing + counted wait in retention local-state loop
# speedup vs baseline: 1.0097x; 1.0042x over previous
.LBB0_271:
	s_and_b32 s6, s19, 3
	s_lshl_b32 s20, s6, 2
	v_mov_b32_e32 v4, s20
	global_load_dword v26, v4, s[12:13]
	global_load_dword v27, v4, s[14:15]
	s_and_b32 s7, s3, 0xffffff80
	v_or_b32_e32 v2, s7, v0
	v_ashrrev_i32_e32 v3, 31, v2
	v_lshlrev_b64 v[4:5], 9, v[2:3]
	s_lshl_b32 s84, s6, 7
	v_lshl_add_u64 v[4:5], s[4:5], 0, v[4:5]
	v_lshl_add_u64 v[4:5], v[4:5], 0, s[84:85]
	v_lshl_add_u64 v[6:7], v[4:5], 0, v[54:55]
	v_lshl_add_u64 v[4:5], v[4:5], 0, v[56:57]
	global_load_dwordx4 v[18:21], v[6:7], off
	global_load_dwordx4 v[22:25], v[4:5], off
	v_lshlrev_b64 v[2:3], 10, v[2:3]
	v_lshl_add_u64 v[2:3], s[8:9], 0, v[2:3]
	s_lshl_b32 s84, s6, 8
	v_lshl_add_u64 v[2:3], v[2:3], 0, s[84:85]
	v_lshl_add_u64 v[4:5], v[2:3], 0, v[54:55]
	v_lshl_add_u64 v[6:7], v[2:3], 0, v[56:57]
	v_lshl_add_u64 v[8:9], v[48:49], 1, v[2:3]
	v_lshl_add_u64 v[2:3], v[50:51], 1, v[2:3]
	global_load_dwordx4 v[14:17], v[4:5], off
	global_load_dwordx4 v[10:13], v[6:7], off
	s_nop 0
	global_load_dwordx4 v[6:9], v[8:9], off
	s_nop 0
	global_load_dwordx4 v[2:5], v[2:3], off
	s_add_i32 s19, s19, s80
	s_add_i32 s3, s3, s18
	s_cmpk_gt_i32 s19, 0x5ff
	s_waitcnt vmcnt(7)
	v_mul_f32_e32 v28, 0x3fb8aa3b, v26
	s_waitcnt vmcnt(6)
	v_mul_f32_e32 v29, 0x3fb8aa3b, v27
	v_fma_f32 v30, v26, s22, -v28
	v_rndne_f32_e32 v31, v28
	v_fma_f32 v32, v27, s22, -v29
	v_rndne_f32_e32 v33, v29
	v_fmac_f32_e32 v30, 0x32a5705f, v26
	v_sub_f32_e32 v28, v28, v31
	v_fmac_f32_e32 v32, 0x32a5705f, v27
	v_sub_f32_e32 v29, v29, v33
	v_add_f32_e32 v28, v28, v30
	v_add_f32_e32 v29, v29, v32
	v_cvt_i32_f32_e32 v31, v31
	v_cvt_i32_f32_e32 v33, v33
	v_exp_f32_e32 v28, v28
	v_exp_f32_e32 v29, v29
	s_waitcnt vmcnt(5)
	v_lshlrev_b32_e32 v30, 16, v18
	v_and_b32_e32 v32, 0xffff0000, v18
	v_lshlrev_b32_e32 v34, 16, v19
	v_and_b32_e32 v35, 0xffff0000, v19
	v_ldexp_f32 v18, v28, v31
	v_ldexp_f32 v19, v29, v33
	v_cmp_ngt_f32_e32 vcc, s23, v27
	v_cmp_ngt_f32_e64 s[6:7], s23, v26
	v_lshlrev_b32_e32 v36, 16, v20
	v_cndmask_b32_e32 v19, 0, v19, vcc
	v_cndmask_b32_e64 v18, 0, v18, s[6:7]
	v_cmp_nlt_f32_e32 vcc, s27, v27
	v_cmp_nlt_f32_e64 s[6:7], s27, v26
	v_and_b32_e32 v37, 0xffff0000, v20
	v_cndmask_b32_e32 v27, v245, v19, vcc
	v_cndmask_b32_e64 v26, v245, v18, s[6:7]
	v_sub_f32_e32 v28, 1.0, v26
	v_sub_f32_e32 v29, 1.0, v27
	v_lshlrev_b32_e32 v38, 16, v21
	v_and_b32_e32 v39, 0xffff0000, v21
	v_add_f32_e32 v31, -1.0, v28
	v_frexp_mant_f32_e32 v33, v28
	v_cvt_f64_f32_e32 v[18:19], v28
	v_add_f32_e32 v44, -1.0, v29
	v_frexp_mant_f32_e32 v45, v29
	v_cvt_f64_f32_e32 v[20:21], v29
	v_sub_f32_e32 v58, v31, v28
	v_frexp_exp_i32_f64_e32 v18, v[18:19]
	v_cmp_gt_f32_e32 vcc, s28, v33
	v_sub_f32_e32 v19, v44, v29
	v_frexp_exp_i32_f64_e32 v20, v[20:21]
	v_cmp_gt_f32_e64 s[6:7], s28, v45
	v_sub_f32_e64 v31, -v26, v31
	v_sub_f32_e64 v33, -v27, v44
	v_add_f32_e32 v21, 1.0, v58
	v_subbrev_co_u32_e32 v18, vcc, 0, v18, vcc
	v_add_f32_e32 v19, 1.0, v19
	v_subbrev_co_u32_e64 v20, vcc, 0, v20, s[6:7]
	v_add_f32_e32 v21, v31, v21
	v_sub_u32_e32 v31, 0, v18
	v_add_f32_e32 v19, v33, v19
	v_sub_u32_e32 v33, 0, v20
	v_cvt_f32_i32_e32 v20, v20
	v_ldexp_f32 v28, v28, v31
	v_ldexp_f32 v29, v29, v33
	v_cvt_f32_i32_e32 v18, v18
	v_ldexp_f32 v21, v21, v31
	v_ldexp_f32 v19, v19, v33
	v_add_f32_e32 v31, -1.0, v28
	v_add_f32_e32 v33, 1.0, v28
	v_add_f32_e32 v44, -1.0, v29
	v_add_f32_e32 v45, 1.0, v29
	v_add_f32_e32 v58, 1.0, v31
	v_add_f32_e32 v59, -1.0, v33
	v_add_f32_e32 v76, 1.0, v44
	v_add_f32_e32 v77, -1.0, v45
	v_sub_f32_e32 v58, v28, v58
	v_sub_f32_e32 v28, v28, v59
	v_sub_f32_e32 v76, v29, v76
	v_sub_f32_e32 v29, v29, v77
	v_mul_f32_e32 v77, 0x3f317218, v20
	v_add_f32_e32 v58, v21, v58
	v_add_f32_e32 v21, v21, v28
	v_add_f32_e32 v76, v19, v76
	v_add_f32_e32 v19, v19, v29
	v_mul_f32_e32 v59, 0x3f317218, v18
	v_fma_f32 v29, v20, s29, -v77
	v_add_f32_e32 v78, v31, v58
	v_add_f32_e32 v79, v33, v21
	v_add_f32_e32 v80, v45, v19
	v_fma_f32 v28, v18, s29, -v59
	v_fmac_f32_e32 v29, 0xb102e308, v20
	v_sub_f32_e32 v20, v78, v31
	v_sub_f32_e32 v31, v79, v33
	v_rcp_f32_e32 v33, v79
	v_rcp_f32_e32 v82, v80
	v_fmac_f32_e32 v28, 0xb102e308, v18
	v_add_f32_e32 v81, v59, v28
	v_sub_f32_e32 v45, v80, v45
	v_add_f32_e32 v83, v77, v29
	v_add_f32_e32 v18, v44, v76
	v_sub_f32_e32 v21, v21, v31
	v_sub_f32_e32 v31, v81, v59
	v_sub_f32_e32 v19, v19, v45
	v_sub_f32_e32 v45, v83, v77
	v_sub_f32_e32 v28, v28, v31
	v_sub_f32_e32 v29, v29, v45
	v_mul_f32_e32 v31, v78, v33
	v_mul_f32_e32 v45, v18, v82
	v_sub_f32_e32 v44, v18, v44
	v_sub_f32_e32 v20, v58, v20
	v_mul_f32_e32 v58, v79, v31
	v_mul_f32_e32 v59, v80, v45
	v_sub_f32_e32 v44, v76, v44
	v_fma_f32 v76, v31, v79, -v58
	v_fma_f32 v77, v45, v80, -v59
	v_fmac_f32_e32 v76, v31, v21
	v_fmac_f32_e32 v77, v45, v19
	v_add_f32_e32 v84, v58, v76
	v_add_f32_e32 v85, v59, v77
	v_sub_f32_e32 v86, v78, v84
	v_sub_f32_e32 v87, v18, v85
	v_sub_f32_e32 v58, v84, v58
	v_sub_f32_e32 v78, v78, v86
	v_sub_f32_e32 v18, v18, v87
	v_sub_f32_e32 v59, v85, v59
	v_sub_f32_e32 v58, v58, v76
	v_sub_f32_e32 v76, v78, v84
	v_sub_f32_e32 v18, v18, v85
	v_sub_f32_e32 v59, v59, v77
	v_add_f32_e32 v20, v20, v76
	v_add_f32_e32 v18, v44, v18
	v_add_f32_e32 v20, v58, v20
	v_add_f32_e32 v18, v59, v18
	v_add_f32_e32 v44, v86, v20
	v_add_f32_e32 v58, v87, v18
	v_mul_f32_e32 v59, v33, v44
	v_mul_f32_e32 v77, v82, v58
	v_sub_f32_e32 v76, v86, v44
	v_sub_f32_e32 v78, v87, v58
	v_mul_f32_e32 v84, v79, v59
	v_mul_f32_e32 v85, v80, v77
	v_add_f32_e32 v20, v20, v76
	v_add_f32_e32 v76, v31, v59
	v_add_f32_e32 v18, v18, v78
	v_add_f32_e32 v78, v45, v77
	v_fma_f32 v79, v59, v79, -v84
	v_fma_f32 v80, v77, v80, -v85
	v_sub_f32_e32 v31, v76, v31
	v_sub_f32_e32 v45, v78, v45
	v_fmac_f32_e32 v79, v59, v21
	v_fmac_f32_e32 v80, v77, v19
	v_sub_f32_e32 v21, v59, v31
	v_sub_f32_e32 v19, v77, v45
	v_add_f32_e32 v31, v84, v79
	v_add_f32_e32 v45, v85, v80
	v_sub_f32_e32 v59, v31, v84
	v_sub_f32_e32 v77, v44, v31
	v_sub_f32_e32 v84, v45, v85
	v_sub_f32_e32 v85, v58, v45
	v_sub_f32_e32 v44, v44, v77
	v_sub_f32_e32 v58, v58, v85
	v_sub_f32_e32 v31, v44, v31
	v_sub_f32_e32 v44, v58, v45
	v_sub_f32_e32 v59, v59, v79
	v_sub_f32_e32 v79, v84, v80
	v_add_f32_e32 v20, v20, v31
	v_add_f32_e32 v18, v18, v44
	v_add_f32_e32 v20, v59, v20
	v_add_f32_e32 v18, v79, v18
	v_add_f32_e32 v20, v77, v20
	v_add_f32_e32 v18, v85, v18
	v_mul_f32_e32 v20, v33, v20
	v_mul_f32_e32 v18, v82, v18
	v_add_f32_e32 v20, v21, v20
	v_add_f32_e32 v18, v19, v18
	v_add_f32_e32 v19, v76, v20
	v_add_f32_e32 v21, v78, v18
	v_mul_f32_e32 v31, v19, v19
	v_sub_f32_e32 v33, v19, v76
	v_mul_f32_e32 v45, v21, v21
	v_fmamk_f32 v76, v31, 0x3e9b6dac, v237
	v_sub_f32_e32 v20, v20, v33
	v_fmamk_f32 v33, v45, 0x3e9b6dac, v237
	v_ldexp_f32 v44, v19, 1
	v_sub_f32_e32 v58, v21, v78
	v_ldexp_f32 v59, v21, 1
	v_mul_f32_e32 v19, v19, v31
	v_mul_f32_e32 v21, v21, v45
	v_fmaak_f32 v31, v31, v76, 0x3f2aaada
	v_fmaak_f32 v33, v45, v33, 0x3f2aaada
	v_mul_f32_e32 v19, v19, v31
	v_mul_f32_e32 v21, v21, v33
	v_add_f32_e32 v31, v44, v19
	v_add_f32_e32 v33, v59, v21
	v_sub_f32_e32 v18, v18, v58
	v_sub_f32_e32 v44, v31, v44
	v_sub_f32_e32 v45, v33, v59
	v_ldexp_f32 v20, v20, 1
	v_ldexp_f32 v18, v18, 1
	v_sub_f32_e32 v19, v19, v44
	v_sub_f32_e32 v21, v21, v45
	v_add_f32_e32 v19, v20, v19
	v_add_f32_e32 v18, v18, v21
	v_add_f32_e32 v20, v31, v19
	v_add_f32_e32 v21, v33, v18
	v_sub_f32_e32 v31, v20, v31
	v_add_f32_e32 v44, v81, v20
	v_sub_f32_e32 v33, v21, v33
	v_add_f32_e32 v45, v83, v21
	v_sub_f32_e32 v19, v19, v31
	v_sub_f32_e32 v31, v44, v81
	v_sub_f32_e32 v18, v18, v33
	v_sub_f32_e32 v33, v45, v83
	v_sub_f32_e32 v58, v44, v31
	v_sub_f32_e32 v20, v20, v31
	v_add_f32_e32 v31, v28, v19
	v_sub_f32_e32 v59, v45, v33
	v_sub_f32_e32 v21, v21, v33
	v_add_f32_e32 v33, v29, v18
	v_sub_f32_e32 v58, v81, v58
	v_sub_f32_e32 v76, v31, v28
	v_sub_f32_e32 v59, v83, v59
	v_sub_f32_e32 v77, v33, v29
	v_add_f32_e32 v20, v20, v58
	v_sub_f32_e32 v58, v31, v76
	v_add_f32_e32 v21, v21, v59
	v_sub_f32_e32 v59, v33, v77
	v_sub_f32_e32 v19, v19, v76
	v_sub_f32_e32 v18, v18, v77
	v_sub_f32_e32 v28, v28, v58
	v_add_f32_e32 v20, v31, v20
	v_sub_f32_e32 v29, v29, v59
	v_add_f32_e32 v21, v33, v21
	v_add_f32_e32 v19, v19, v28
	v_add_f32_e32 v28, v44, v20
	v_add_f32_e32 v18, v18, v29
	v_add_f32_e32 v29, v45, v21
	v_sub_f32_e32 v31, v28, v44
	v_sub_f32_e32 v33, v29, v45
	v_sub_f32_e32 v20, v20, v31
	v_sub_f32_e32 v21, v21, v33
	v_add_f32_e32 v19, v19, v20
	v_add_f32_e32 v18, v18, v21
	v_add_f32_e32 v19, v28, v19
	v_add_f32_e32 v18, v29, v18
	v_cmp_nlt_f32_e32 vcc, 1.0, v27
	v_cmp_nlt_f32_e64 s[6:7], 1.0, v26
	v_cmp_lt_f32_e64 s[20:21], |v26|, s30
	v_cndmask_b32_e32 v18, v241, v18, vcc
	v_cndmask_b32_e64 v19, v241, v19, s[6:7]
	v_cmp_neq_f32_e32 vcc, 1.0, v27
	v_cmp_neq_f32_e64 s[6:7], 1.0, v26
	s_waitcnt vmcnt(4)
	v_lshlrev_b32_e32 v40, 16, v22
	v_cndmask_b32_e32 v18, v238, v18, vcc
	v_cndmask_b32_e64 v19, v238, v19, s[6:7]
	v_cmp_lt_f32_e64 s[6:7], |v27|, s30
	v_cndmask_b32_e64 v19, v19, -v26, s[20:21]
	v_mul_f32_e32 v19, 0x3fb8aa3b, v19
	v_cndmask_b32_e64 v18, v18, -v27, s[6:7]
	v_mul_f32_e32 v18, 0x3fb8aa3b, v18
	v_mul_f32_e32 v19, v19, v60
	v_mul_f32_e32 v18, v18, v61
	v_exp_f32_e32 v19, v19
	v_exp_f32_e32 v18, v18
	v_and_b32_e32 v22, 0xffff0000, v22
	v_lshlrev_b32_e32 v41, 16, v23
	v_and_b32_e32 v23, 0xffff0000, v23
	v_lshlrev_b32_e32 v42, 16, v24
	v_and_b32_e32 v24, 0xffff0000, v24
	v_lshlrev_b32_e32 v43, 16, v25
	v_and_b32_e32 v25, 0xffff0000, v25
	v_mul_f32_e32 v20, v19, v30
	v_mul_f32_e32 v21, v18, v30
	v_mul_f32_e32 v26, v19, v32
	v_mul_f32_e32 v27, v18, v32
	v_mul_f32_e32 v28, v19, v34
	v_mul_f32_e32 v29, v18, v34
	v_mul_f32_e32 v30, v19, v35
	v_mul_f32_e32 v31, v18, v35
	v_mul_f32_e32 v32, v19, v36
	v_mul_f32_e32 v33, v18, v36
	v_mul_f32_e32 v34, v19, v37
	v_mul_f32_e32 v35, v18, v37
	v_mul_f32_e32 v36, v19, v38
	v_mul_f32_e32 v37, v18, v38
	v_mul_f32_e32 v38, v19, v39
	v_mul_f32_e32 v39, v18, v39
	v_mul_f32_e32 v44, v19, v40
	v_mul_f32_e32 v40, v18, v40
	v_mul_f32_e32 v45, v19, v22
	v_mul_f32_e32 v22, v18, v22
	v_mul_f32_e32 v58, v19, v41
	v_mul_f32_e32 v41, v18, v41
	v_mul_f32_e32 v59, v19, v23
	v_mul_f32_e32 v23, v18, v23
	v_mul_f32_e32 v76, v19, v42
	v_mul_f32_e32 v42, v18, v42
	v_mul_f32_e32 v77, v19, v24
	v_mul_f32_e32 v24, v18, v24
	v_mul_f32_e32 v78, v19, v43
	v_mul_f32_e32 v43, v18, v43
	v_mul_f32_e32 v19, v19, v25
	v_mul_f32_e32 v18, v18, v25
	v_bfe_u32 v25, v20, 16, 1
	v_bfe_u32 v79, v21, 16, 1
	v_bfe_u32 v80, v26, 16, 1
	v_bfe_u32 v81, v27, 16, 1
	v_bfe_u32 v82, v28, 16, 1
	v_bfe_u32 v83, v29, 16, 1
	v_bfe_u32 v84, v30, 16, 1
	v_bfe_u32 v85, v31, 16, 1
	v_bfe_u32 v86, v32, 16, 1
	v_bfe_u32 v87, v33, 16, 1
	v_bfe_u32 v88, v34, 16, 1
	v_bfe_u32 v89, v35, 16, 1
	v_bfe_u32 v90, v36, 16, 1
	v_bfe_u32 v91, v37, 16, 1
	v_bfe_u32 v92, v38, 16, 1
	v_bfe_u32 v93, v39, 16, 1
	v_bfe_u32 v94, v44, 16, 1
	v_bfe_u32 v95, v40, 16, 1
	v_bfe_u32 v97, v22, 16, 1
	v_bfe_u32 v99, v41, 16, 1
	v_bfe_u32 v101, v23, 16, 1
	v_bfe_u32 v105, v24, 16, 1
	v_bfe_u32 v108, v19, 16, 1
	v_bfe_u32 v109, v18, 16, 1
	v_bfe_u32 v96, v45, 16, 1
	v_bfe_u32 v98, v58, 16, 1
	v_bfe_u32 v100, v59, 16, 1
	v_bfe_u32 v102, v76, 16, 1
	v_bfe_u32 v103, v42, 16, 1
	v_bfe_u32 v104, v77, 16, 1
	v_bfe_u32 v106, v78, 16, 1
	v_bfe_u32 v107, v43, 16, 1
	v_add3_u32 v20, v20, v25, s56
	v_add3_u32 v21, v21, v79, s56
	v_add3_u32 v25, v26, v80, s56
	v_add3_u32 v26, v27, v81, s56
	v_add3_u32 v27, v28, v82, s56
	v_add3_u32 v28, v29, v83, s56
	v_add3_u32 v29, v30, v84, s56
	v_add3_u32 v30, v31, v85, s56
	v_add3_u32 v31, v32, v86, s56
	v_add3_u32 v32, v33, v87, s56
	v_add3_u32 v33, v34, v88, s56
	v_add3_u32 v34, v35, v89, s56
	v_add3_u32 v35, v36, v90, s56
	v_add3_u32 v36, v37, v91, s56
	v_add3_u32 v37, v38, v92, s56
	v_add3_u32 v38, v39, v93, s56
	v_add3_u32 v39, v44, v94, s56
	v_add3_u32 v40, v40, v95, s56
	v_add3_u32 v22, v22, v97, s56
	v_add3_u32 v41, v41, v99, s56
	v_add3_u32 v23, v23, v101, s56
	v_add3_u32 v24, v24, v105, s56
	v_add3_u32 v19, v19, v108, s56
	v_add3_u32 v18, v18, v109, s56
	v_add3_u32 v44, v45, v96, s56
	v_add3_u32 v45, v58, v98, s56
	v_add3_u32 v58, v59, v100, s56
	v_add3_u32 v59, v76, v102, s56
	v_add3_u32 v42, v42, v103, s56
	v_add3_u32 v76, v77, v104, s56
	v_add3_u32 v77, v78, v106, s56
	v_add3_u32 v43, v43, v107, s56
	ds_write_b16_d16_hi v47, v20
	ds_write_b16_d16_hi v47, v21 offset:17408
	ds_write_b16_d16_hi v47, v25 offset:272
	ds_write_b16_d16_hi v47, v26 offset:17680
	ds_write_b16_d16_hi v47, v27 offset:544
	ds_write_b16_d16_hi v47, v28 offset:17952
	ds_write_b16_d16_hi v47, v29 offset:816
	ds_write_b16_d16_hi v47, v30 offset:18224
	ds_write_b16_d16_hi v47, v31 offset:1088
	ds_write_b16_d16_hi v47, v32 offset:18496
	ds_write_b16_d16_hi v47, v33 offset:1360
	ds_write_b16_d16_hi v47, v34 offset:18768
	ds_write_b16_d16_hi v47, v35 offset:1632
	ds_write_b16_d16_hi v47, v36 offset:19040
	ds_write_b16_d16_hi v62, v37
	ds_write_b16_d16_hi v62, v38 offset:17408
	ds_write_b16_d16_hi v63, v39
	ds_write_b16_d16_hi v63, v40 offset:17408
	ds_write_b16_d16_hi v63, v44 offset:272
	ds_write_b16_d16_hi v63, v22 offset:17680
	ds_write_b16_d16_hi v63, v45 offset:544
	ds_write_b16_d16_hi v63, v41 offset:17952
	ds_write_b16_d16_hi v63, v58 offset:816
	ds_write_b16_d16_hi v63, v23 offset:18224
	ds_write_b16_d16_hi v63, v59 offset:1088
	ds_write_b16_d16_hi v63, v42 offset:18496
	ds_write_b16_d16_hi v63, v76 offset:1360
	ds_write_b16_d16_hi v63, v24 offset:18768
	ds_write_b16_d16_hi v63, v77 offset:1632
	ds_write_b16_d16_hi v63, v43 offset:19040
	ds_write_b16_d16_hi v64, v19
	ds_write_b16_d16_hi v64, v18 offset:17408
	s_waitcnt vmcnt(3)
	ds_write_b16 v65, v14 offset:34816
	ds_write_b16_d16_hi v65, v14 offset:35088
	ds_write_b16 v66, v15 offset:34816
	ds_write_b16_d16_hi v66, v15 offset:35088
	ds_write_b16 v67, v16 offset:34816
	ds_write_b16_d16_hi v67, v16 offset:35088
	ds_write_b16 v68, v17 offset:34816
	ds_write_b16_d16_hi v68, v17 offset:35088
	s_waitcnt vmcnt(2)
	ds_write_b16 v69, v10 offset:34816
	ds_write_b16_d16_hi v69, v10 offset:35088
	ds_write_b16 v70, v11 offset:34816
	ds_write_b16_d16_hi v70, v11 offset:35088
	ds_write_b16 v71, v12 offset:34816
	ds_write_b16_d16_hi v71, v12 offset:35088
	ds_write_b16 v72, v13 offset:34816
	ds_write_b16_d16_hi v72, v13 offset:35088
	s_waitcnt vmcnt(1)
	ds_write_b16 v73, v6 offset:34816
	ds_write_b16_d16_hi v73, v6 offset:35088
	ds_write_b16 v73, v7 offset:35360
	ds_write_b16_d16_hi v73, v7 offset:35632
	ds_write_b16 v73, v8 offset:35904
	ds_write_b16_d16_hi v73, v8 offset:36176
	ds_write_b16 v73, v9 offset:36448
	ds_write_b16_d16_hi v73, v9 offset:36720
	s_waitcnt vmcnt(0)
	ds_write_b16 v74, v2 offset:34816
	ds_write_b16_d16_hi v74, v2 offset:35088
	ds_write_b16 v74, v3 offset:35360
	ds_write_b16_d16_hi v74, v3 offset:35632
	ds_write_b16 v74, v4 offset:35904
	ds_write_b16_d16_hi v74, v4 offset:36176
	ds_write_b16 v74, v5 offset:36448
	ds_write_b16_d16_hi v74, v5 offset:36720
	s_waitcnt lgkmcnt(0)
	s_barrier
	ds_read_b128 v[2:5], v75
	ds_read_b128 v[6:9], v46 offset:34816
	ds_read_b128 v[10:13], v46 offset:34880
	ds_read_b128 v[14:17], v75 offset:64
	ds_read_b128 v[18:21], v75 offset:17408
	ds_read_b128 v[22:25], v75 offset:17472
	ds_read_b128 v[26:29], v75 offset:4352
	ds_read_b128 v[30:33], v75 offset:4416
	ds_read_b128 v[34:37], v75 offset:21760
	ds_read_b128 v[38:41], v75 offset:21824
	s_waitcnt lgkmcnt(5)
	v_mfma_f32_16x16x32_bf16 v[18:21], v[18:21], v[6:9], 0
	ds_read_b128 v[42:45], v75 offset:8704
	ds_read_b128 v[76:79], v75 offset:8768
	ds_read_b128 v[80:83], v75 offset:26112
	ds_read_b128 v[84:87], v75 offset:26176
	ds_read_b128 v[88:91], v75 offset:13056
	ds_read_b128 v[92:95], v75 offset:13120
	s_waitcnt lgkmcnt(9)
	v_mfma_f32_16x16x32_bf16 v[26:29], v[26:29], v[6:9], 0
	ds_read_b128 v[96:99], v75 offset:30464
	ds_read_b128 v[100:103], v75 offset:30528
	v_add_co_u32_e32 v58, vcc, s31, v52
	s_waitcnt lgkmcnt(9)
	v_mfma_f32_16x16x32_bf16 v[34:37], v[34:37], v[6:9], 0
	v_addc_co_u32_e32 v59, vcc, 0, v53, vcc
	v_mfma_f32_16x16x32_bf16 v[18:21], v[22:25], v[10:13], v[18:21]
	v_mfma_f32_16x16x32_bf16 v[22:25], v[30:33], v[10:13], v[26:29]
	s_waitcnt lgkmcnt(8)
	v_mfma_f32_16x16x32_bf16 v[26:29], v[38:41], v[10:13], v[34:37]
	ds_read_b128 v[38:41], v75 offset:128
	v_mfma_f32_16x16x32_bf16 v[2:5], v[2:5], v[6:9], 0
	s_waitcnt lgkmcnt(8)
	v_mfma_f32_16x16x32_bf16 v[42:45], v[42:45], v[6:9], 0
	s_waitcnt lgkmcnt(6)
	v_mfma_f32_16x16x32_bf16 v[80:83], v[80:83], v[6:9], 0
	s_waitcnt lgkmcnt(4)
	v_mfma_f32_16x16x32_bf16 v[88:91], v[88:91], v[6:9], 0
	s_waitcnt lgkmcnt(2)
	v_mfma_f32_16x16x32_bf16 v[6:9], v[96:99], v[6:9], 0
	v_mfma_f32_16x16x32_bf16 v[14:17], v[14:17], v[10:13], v[2:5]
	v_mfma_f32_16x16x32_bf16 v[30:33], v[76:79], v[10:13], v[42:45]
	v_mfma_f32_16x16x32_bf16 v[34:37], v[84:87], v[10:13], v[80:83]
	v_mfma_f32_16x16x32_bf16 v[42:45], v[92:95], v[10:13], v[88:91]
	s_waitcnt lgkmcnt(1)
	v_mfma_f32_16x16x32_bf16 v[6:9], v[100:103], v[10:13], v[6:9]
	ds_read_b128 v[10:13], v46 offset:34944
	ds_read_b128 v[2:5], v46 offset:35008
	ds_read_b128 v[76:79], v75 offset:192
	s_waitcnt lgkmcnt(2)
	v_mfma_f32_16x16x32_bf16 v[14:17], v[38:41], v[10:13], v[14:17]
	ds_read_b128 v[38:41], v75 offset:17536
	ds_read_b128 v[80:83], v75 offset:17600
	s_waitcnt lgkmcnt(1)
	v_mfma_f32_16x16x32_bf16 v[18:21], v[38:41], v[10:13], v[18:21]
	ds_read_b128 v[38:41], v75 offset:4480
	ds_read_b128 v[84:87], v75 offset:4544
	s_waitcnt lgkmcnt(1)
	v_mfma_f32_16x16x32_bf16 v[88:91], v[38:41], v[10:13], v[22:25]
	s_nop 2
	ds_read_b128 v[22:25], v75 offset:21888
	ds_read_b128 v[92:95], v75 offset:21952
	s_waitcnt lgkmcnt(1)
	v_mfma_f32_16x16x32_bf16 v[96:99], v[22:25], v[10:13], v[26:29]
	ds_read_b128 v[22:25], v75 offset:8832
	ds_read_b128 v[100:103], v75 offset:8896
	s_waitcnt lgkmcnt(1)
	v_mfma_f32_16x16x32_bf16 v[104:107], v[22:25], v[10:13], v[30:33]
	ds_read_b128 v[22:25], v75 offset:26240
	ds_read_b128 v[108:111], v75 offset:26304
	s_waitcnt lgkmcnt(1)
	v_mfma_f32_16x16x32_bf16 v[112:115], v[22:25], v[10:13], v[34:37]
	ds_read_b128 v[22:25], v75 offset:13184
	ds_read_b128 v[38:41], v75 offset:13248
	s_waitcnt lgkmcnt(1)
	v_mfma_f32_16x16x32_bf16 v[42:45], v[22:25], v[10:13], v[42:45]
	ds_read_b128 v[22:25], v75 offset:30592
	ds_read_b128 v[30:33], v75 offset:30656
	s_waitcnt lgkmcnt(1)
	v_mfma_f32_16x16x32_bf16 v[34:37], v[22:25], v[10:13], v[6:9]
	v_mfma_f32_16x16x32_bf16 v[26:29], v[76:79], v[2:5], v[14:17]
	v_mfma_f32_16x16x32_bf16 v[22:25], v[80:83], v[2:5], v[18:21]
	v_mfma_f32_16x16x32_bf16 v[18:21], v[84:87], v[2:5], v[88:91]
	s_nop 5
	v_cvt_pk_bf16_f32 v26, v26, v27
	v_cvt_pk_bf16_f32 v27, v28, v29
	v_cvt_pk_bf16_f32 v22, v22, v23
	v_mfma_f32_16x16x32_bf16 v[14:17], v[92:95], v[2:5], v[96:99]
	v_cvt_pk_bf16_f32 v23, v24, v25
	v_cvt_pk_bf16_f32 v18, v18, v19
	v_cvt_pk_bf16_f32 v19, v20, v21
	v_mfma_f32_16x16x32_bf16 v[10:13], v[100:103], v[2:5], v[104:107]
	v_mfma_f32_16x16x32_bf16 v[6:9], v[108:111], v[2:5], v[112:115]
	s_nop 2
	v_cvt_pk_bf16_f32 v14, v14, v15
	v_cvt_pk_bf16_f32 v15, v16, v17
	s_nop 1
	v_cvt_pk_bf16_f32 v10, v10, v11
	v_mfma_f32_16x16x32_bf16 v[38:41], v[38:41], v[2:5], v[42:45]
	v_cvt_pk_bf16_f32 v11, v12, v13
	v_cvt_pk_bf16_f32 v6, v6, v7
	v_cvt_pk_bf16_f32 v7, v8, v9
	s_waitcnt lgkmcnt(0)
	v_mfma_f32_16x16x32_bf16 v[2:5], v[30:33], v[2:5], v[34:37]
	s_nop 2
	v_cvt_pk_bf16_f32 v8, v38, v39
	v_cvt_pk_bf16_f32 v9, v40, v41
	s_nop 2
	v_cvt_pk_bf16_f32 v2, v2, v3
	v_cvt_pk_bf16_f32 v3, v4, v5
	global_store_dwordx2 v[52:53], v[26:27], off
	global_store_dwordx2 v[58:59], v[22:23], off
	global_store_dwordx2 v[52:53], v[18:19], off offset:32
	global_store_dwordx2 v[58:59], v[14:15], off offset:32
	global_store_dwordx2 v[52:53], v[10:11], off offset:64
	global_store_dwordx2 v[58:59], v[6:7], off offset:64
	global_store_dwordx2 v[52:53], v[8:9], off offset:96
	global_store_dwordx2 v[58:59], v[2:3], off offset:96
	v_lshl_add_u64 v[52:53], v[52:53], 0, s[16:17]
	s_barrier
	s_cbranch_scc0 .LBB0_271
	s_movk_i32 s59, 0x4000
	s_mov_b64 s[4:5], s[10:11]
	s_mov_b32 s62, s25
	s_mov_b32 s60, s24
	s_mov_b32 s61, s26
	s_mov_b32 s93, s34
	s_branch .LBB0_274

.LBB0_289:
	s_ashr_i32 s17, s16, 31
	s_lshl_b64 s[18:19], s[16:17], 19
	s_add_u32 s18, s30, s18
	s_addc_u32 s19, s31, s19
	s_and_b64 s[20:21], s[6:7], exec
	s_cselect_b32 s17, s19, s25
	s_cselect_b32 s46, s18, s24
	s_ashr_i32 s15, s14, 31
	s_lshl_b64 s[20:21], s[14:15], 19
	s_add_u32 s20, s34, s20
	s_addc_u32 s21, s35, s21
	s_and_b64 s[28:29], s[6:7], exec
	s_cselect_b32 s15, s21, s27
	s_cselect_b32 s47, s20, s26
	s_add_u32 s24, s24, 0x40080
	s_addc_u32 s25, s25, 0
	s_add_u32 s48, s26, 0x100
	v_mov_b32_e32 v2, 0
	s_addc_u32 s49, s27, 0
	s_mov_b32 s50, -2
	v_mov_b32_e32 v3, v2
	v_mov_b64_e32 v[4:5], 0
	v_mov_b64_e32 v[6:7], 0
	v_mov_b64_e32 v[8:9], 0
	v_mov_b64_e32 v[18:19], 0
	v_mov_b64_e32 v[20:21], 0
	v_mov_b64_e32 v[22:23], 0
	v_mov_b64_e32 v[24:25], 0
	v_mov_b64_e32 v[34:35], 0
	v_mov_b64_e32 v[36:37], 0
	v_mov_b64_e32 v[38:39], 0
	v_mov_b64_e32 v[40:41], 0
	v_mov_b64_e32 v[50:51], 0
	v_mov_b64_e32 v[52:53], 0
	v_mov_b64_e32 v[54:55], 0
	v_mov_b64_e32 v[56:57], 0
	v_mov_b64_e32 v[10:11], 0
	v_mov_b64_e32 v[12:13], 0
	v_mov_b64_e32 v[14:15], 0
	v_mov_b64_e32 v[16:17], 0
	v_mov_b64_e32 v[26:27], 0
	v_mov_b64_e32 v[28:29], 0
	v_mov_b64_e32 v[30:31], 0
	v_mov_b64_e32 v[32:33], 0
	v_mov_b64_e32 v[42:43], 0
	v_mov_b64_e32 v[44:45], 0
	v_mov_b64_e32 v[46:47], 0
	v_mov_b64_e32 v[48:49], 0
	v_mov_b64_e32 v[58:59], 0
	v_mov_b64_e32 v[60:61], 0
	v_mov_b64_e32 v[62:63], 0
	v_mov_b64_e32 v[64:65], 0
	v_mov_b64_e32 v[66:67], 0
	v_mov_b64_e32 v[68:69], 0
	v_mov_b64_e32 v[70:71], 0
	v_mov_b64_e32 v[72:73], 0
	v_mov_b64_e32 v[82:83], 0
	v_mov_b64_e32 v[84:85], 0
	v_mov_b64_e32 v[86:87], 0
	v_mov_b64_e32 v[88:89], 0
	v_mov_b64_e32 v[98:99], 0
	v_mov_b64_e32 v[100:101], 0
	v_mov_b64_e32 v[102:103], 0
	v_mov_b64_e32 v[104:105], 0
	v_mov_b64_e32 v[114:115], 0
	v_mov_b64_e32 v[116:117], 0
	v_mov_b64_e32 v[118:119], 0
	v_mov_b64_e32 v[120:121], 0
	v_mov_b64_e32 v[74:75], 0
	v_mov_b64_e32 v[76:77], 0
	v_mov_b64_e32 v[78:79], 0
	v_mov_b64_e32 v[80:81], 0
	v_mov_b64_e32 v[90:91], 0
	v_mov_b64_e32 v[92:93], 0
	v_mov_b64_e32 v[94:95], 0
	v_mov_b64_e32 v[96:97], 0
	v_mov_b64_e32 v[106:107], 0
	v_mov_b64_e32 v[108:109], 0
	v_mov_b64_e32 v[110:111], 0
	v_mov_b64_e32 v[112:113], 0
	v_mov_b64_e32 v[122:123], 0
	v_mov_b64_e32 v[124:125], 0
	v_mov_b64_e32 v[126:127], 0
	v_mov_b64_e32 v[128:129], 0
	v_add_u32_e32 v188, 0x10000, v173

.LBB0_330:
	s_add_u32 s30, s30, 0x80
	s_addc_u32 s31, s31, 0
	s_add_u32 s66, s34, 0x100
	v_mov_b32_e32 v2, 0
	s_addc_u32 s67, s35, 0
	s_mov_b32 s34, 0
	v_mov_b32_e32 v3, v2
	v_mov_b64_e32 v[4:5], 0
	v_mov_b64_e32 v[6:7], 0
	v_mov_b64_e32 v[8:9], 0
	v_mov_b64_e32 v[18:19], 0
	v_mov_b64_e32 v[20:21], 0
	v_mov_b64_e32 v[22:23], 0
	v_mov_b64_e32 v[24:25], 0
	v_mov_b64_e32 v[34:35], 0
	v_mov_b64_e32 v[36:37], 0
	v_mov_b64_e32 v[38:39], 0
	v_mov_b64_e32 v[40:41], 0
	v_mov_b64_e32 v[50:51], 0
	v_mov_b64_e32 v[52:53], 0
	v_mov_b64_e32 v[54:55], 0
	v_mov_b64_e32 v[56:57], 0
	v_mov_b64_e32 v[10:11], 0
	v_mov_b64_e32 v[12:13], 0
	v_mov_b64_e32 v[14:15], 0
	v_mov_b64_e32 v[16:17], 0
	v_mov_b64_e32 v[26:27], 0
	v_mov_b64_e32 v[28:29], 0
	v_mov_b64_e32 v[30:31], 0
	v_mov_b64_e32 v[32:33], 0
	v_mov_b64_e32 v[42:43], 0
	v_mov_b64_e32 v[44:45], 0
	v_mov_b64_e32 v[46:47], 0
	v_mov_b64_e32 v[48:49], 0
	v_mov_b64_e32 v[58:59], 0
	v_mov_b64_e32 v[60:61], 0
	v_mov_b64_e32 v[62:63], 0
	v_mov_b64_e32 v[64:65], 0
	v_mov_b64_e32 v[66:67], 0
	v_mov_b64_e32 v[68:69], 0
	v_mov_b64_e32 v[70:71], 0
	v_mov_b64_e32 v[72:73], 0
	v_mov_b64_e32 v[82:83], 0
	v_mov_b64_e32 v[84:85], 0
	v_mov_b64_e32 v[86:87], 0
	v_mov_b64_e32 v[88:89], 0
	v_mov_b64_e32 v[98:99], 0
	v_mov_b64_e32 v[100:101], 0
	v_mov_b64_e32 v[102:103], 0
	v_mov_b64_e32 v[104:105], 0
	v_mov_b64_e32 v[114:115], 0
	v_mov_b64_e32 v[116:117], 0
	v_mov_b64_e32 v[118:119], 0
	v_mov_b64_e32 v[120:121], 0
	v_mov_b64_e32 v[74:75], 0
	v_mov_b64_e32 v[76:77], 0
	v_mov_b64_e32 v[78:79], 0
	v_mov_b64_e32 v[80:81], 0
	v_mov_b64_e32 v[90:91], 0
	v_mov_b64_e32 v[92:93], 0
	v_mov_b64_e32 v[94:95], 0
	v_mov_b64_e32 v[96:97], 0
	v_mov_b64_e32 v[106:107], 0
	v_mov_b64_e32 v[108:109], 0
	v_mov_b64_e32 v[110:111], 0
	v_mov_b64_e32 v[112:113], 0
	v_mov_b64_e32 v[122:123], 0
	v_mov_b64_e32 v[124:125], 0
	v_mov_b64_e32 v[126:127], 0
	v_mov_b64_e32 v[128:129], 0
	v_add_u32_e32 v210, 0x10000, v245

.LBB0_393:
	s_ashr_i32 s31, s30, 31
	s_lshl_b64 s[14:15], s[30:31], 19
	s_add_u32 s34, s64, s14
	s_addc_u32 s35, s65, s15
	s_and_b64 s[14:15], s[8:9], exec
	s_cselect_b32 s31, s35, s11
	s_cselect_b32 s38, s34, s10
	s_ashr_i32 s29, s28, 31
	s_lshl_b64 s[14:15], s[28:29], 19
	s_add_u32 s36, s66, s14
	s_addc_u32 s37, s67, s15
	s_and_b64 s[14:15], s[8:9], exec
	s_cselect_b32 s29, s37, s13
	s_cselect_b32 s39, s36, s12
	s_add_u32 s10, s10, 0x40080
	s_addc_u32 s11, s11, 0
	s_add_u32 s44, s12, 0x100
	v_mov_b32_e32 v2, 0
	s_addc_u32 s45, s13, 0
	s_mov_b32 s46, -2
	v_mov_b32_e32 v3, v2
	v_mov_b64_e32 v[4:5], 0
	v_mov_b64_e32 v[6:7], 0
	v_mov_b64_e32 v[8:9], 0
	v_mov_b64_e32 v[18:19], 0
	v_mov_b64_e32 v[20:21], 0
	v_mov_b64_e32 v[22:23], 0
	v_mov_b64_e32 v[24:25], 0
	v_mov_b64_e32 v[34:35], 0
	v_mov_b64_e32 v[36:37], 0
	v_mov_b64_e32 v[38:39], 0
	v_mov_b64_e32 v[40:41], 0
	v_mov_b64_e32 v[66:67], 0
	v_mov_b64_e32 v[68:69], 0
	v_mov_b64_e32 v[70:71], 0
	v_mov_b64_e32 v[72:73], 0
	v_mov_b64_e32 v[10:11], 0
	v_mov_b64_e32 v[12:13], 0
	v_mov_b64_e32 v[14:15], 0
	v_mov_b64_e32 v[16:17], 0
	v_mov_b64_e32 v[26:27], 0
	v_mov_b64_e32 v[28:29], 0
	v_mov_b64_e32 v[30:31], 0
	v_mov_b64_e32 v[32:33], 0
	v_mov_b64_e32 v[42:43], 0
	v_mov_b64_e32 v[44:45], 0
	v_mov_b64_e32 v[46:47], 0
	v_mov_b64_e32 v[48:49], 0
	v_mov_b64_e32 v[74:75], 0
	v_mov_b64_e32 v[76:77], 0
	v_mov_b64_e32 v[78:79], 0
	v_mov_b64_e32 v[80:81], 0
	v_mov_b64_e32 v[82:83], 0
	v_mov_b64_e32 v[84:85], 0
	v_mov_b64_e32 v[86:87], 0
	v_mov_b64_e32 v[88:89], 0
	v_mov_b64_e32 v[98:99], 0
	v_mov_b64_e32 v[100:101], 0
	v_mov_b64_e32 v[102:103], 0
	v_mov_b64_e32 v[104:105], 0
	v_mov_b64_e32 v[114:115], 0
	v_mov_b64_e32 v[116:117], 0
	v_mov_b64_e32 v[118:119], 0
	v_mov_b64_e32 v[120:121], 0
	v_mov_b64_e32 v[130:131], 0
	v_mov_b64_e32 v[132:133], 0
	v_mov_b64_e32 v[134:135], 0
	v_mov_b64_e32 v[136:137], 0
	v_mov_b64_e32 v[90:91], 0
	v_mov_b64_e32 v[92:93], 0
	v_mov_b64_e32 v[94:95], 0
	v_mov_b64_e32 v[96:97], 0
	v_mov_b64_e32 v[106:107], 0
	v_mov_b64_e32 v[108:109], 0
	v_mov_b64_e32 v[110:111], 0
	v_mov_b64_e32 v[112:113], 0
	v_mov_b64_e32 v[122:123], 0
	v_mov_b64_e32 v[124:125], 0
	v_mov_b64_e32 v[126:127], 0
	v_mov_b64_e32 v[128:129], 0
	v_mov_b64_e32 v[138:139], 0
	v_mov_b64_e32 v[140:141], 0
	v_mov_b64_e32 v[142:143], 0
	v_mov_b64_e32 v[144:145], 0
	v_add_u32_e32 v216, 0x10000, v182

.LBB0_457:
	s_ashr_i32 s27, s26, 31
	s_lshl_b64 s[28:29], s[26:27], s50
	s_add_u32 s28, s41, s28
	s_addc_u32 s29, s42, s29
	s_and_b64 s[30:31], s[6:7], exec
	s_cselect_b32 s27, s29, s37
	s_cselect_b32 s35, s28, s36
	s_ashr_i32 s25, s24, 31
	s_lshl_b64 s[30:31], s[24:25], s50
	s_add_u32 s30, s3, s30
	s_addc_u32 s31, s43, s31
	s_and_b64 s[66:67], s[6:7], exec
	s_cselect_b32 s25, s31, s39
	s_cselect_b32 s66, s30, s38
	s_add_u32 s36, s36, 0x80
	s_addc_u32 s37, s37, 0
	s_add_u32 s67, s38, 0x100
	v_mov_b32_e32 v2, 0
	s_addc_u32 s68, s39, 0
	s_mov_b32 s38, 0
	v_mov_b32_e32 v3, v2
	v_mov_b64_e32 v[4:5], 0
	v_mov_b64_e32 v[6:7], 0
	v_mov_b64_e32 v[8:9], 0
	v_mov_b64_e32 v[10:11], 0
	v_mov_b64_e32 v[12:13], 0
	v_mov_b64_e32 v[14:15], 0
	v_mov_b64_e32 v[16:17], 0
	v_mov_b64_e32 v[18:19], 0
	v_mov_b64_e32 v[20:21], 0
	v_mov_b64_e32 v[22:23], 0
	v_mov_b64_e32 v[24:25], 0
	v_mov_b64_e32 v[26:27], 0
	v_mov_b64_e32 v[28:29], 0
	v_mov_b64_e32 v[30:31], 0
	v_mov_b64_e32 v[32:33], 0
	v_mov_b64_e32 v[42:43], 0
	v_mov_b64_e32 v[44:45], 0
	v_mov_b64_e32 v[46:47], 0
	v_mov_b64_e32 v[48:49], 0
	v_mov_b64_e32 v[58:59], 0
	v_mov_b64_e32 v[60:61], 0
	v_mov_b64_e32 v[66:67], 0
	v_mov_b64_e32 v[68:69], 0
	v_mov_b64_e32 v[78:79], 0
	v_mov_b64_e32 v[80:81], 0
	v_mov_b64_e32 v[86:87], 0
	v_mov_b64_e32 v[88:89], 0
	v_mov_b64_e32 v[90:91], 0
	v_mov_b64_e32 v[92:93], 0
	v_mov_b64_e32 v[94:95], 0
	v_mov_b64_e32 v[96:97], 0
	v_mov_b64_e32 v[34:35], 0
	v_mov_b64_e32 v[36:37], 0
	v_mov_b64_e32 v[38:39], 0
	v_mov_b64_e32 v[40:41], 0
	v_mov_b64_e32 v[50:51], 0
	v_mov_b64_e32 v[52:53], 0
	v_mov_b64_e32 v[54:55], 0
	v_mov_b64_e32 v[56:57], 0
	v_mov_b64_e32 v[62:63], 0
	v_mov_b64_e32 v[64:65], 0
	v_mov_b64_e32 v[70:71], 0
	v_mov_b64_e32 v[72:73], 0
	v_mov_b64_e32 v[74:75], 0
	v_mov_b64_e32 v[76:77], 0
	v_mov_b64_e32 v[82:83], 0
	v_mov_b64_e32 v[84:85], 0
	v_mov_b64_e32 v[98:99], 0
	v_mov_b64_e32 v[100:101], 0
	v_mov_b64_e32 v[102:103], 0
	v_mov_b64_e32 v[104:105], 0
	v_mov_b64_e32 v[106:107], 0
	v_mov_b64_e32 v[108:109], 0
	v_mov_b64_e32 v[110:111], 0
	v_mov_b64_e32 v[112:113], 0
	v_mov_b64_e32 v[114:115], 0
	v_mov_b64_e32 v[116:117], 0
	v_mov_b64_e32 v[118:119], 0
	v_mov_b64_e32 v[120:121], 0
	v_mov_b64_e32 v[122:123], 0
	v_mov_b64_e32 v[124:125], 0
	v_mov_b64_e32 v[126:127], 0
	v_mov_b64_e32 v[128:129], 0
	v_add_u32_e32 v202, 0x10000, v201
